# hyena ctx item: conv dot-product loops 8 taps per trip with wave-uniform bounds (was one LDS latency per tap)
# baseline (speedup 1.0000x reference)
.LBB0_954:
	v_readfirstlane_b32 s12, v21
	s_lshr_b32 s12, s12, 2
	v_mov_b32_e32 v33, v19
	v_mov_b32_e32 v35, v21
	v_add_u32_e32 v34, 0x804, v21
	s_mov_b32 s13, 0
.Lhc1_a:
	s_cmp_ge_u32 s13, s12
	s_cbranch_scc1 .Lhc1_b
	ds_read_b128 v[40:43], v33
	ds_read_b128 v[44:47], v33 offset:16
	ds_read2_b32 v[48:49], v34 offset0:7 offset1:6
	ds_read2_b32 v[50:51], v34 offset0:5 offset1:4
	ds_read2_b32 v[52:53], v34 offset0:3 offset1:2
	ds_read2_b32 v[54:55], v34 offset0:1 offset1:0
	v_add_u32_e32 v33, 32, v33
	v_add_u32_e32 v34, 0xffffffe0, v34
	s_add_u32 s13, s13, 8
	s_waitcnt lgkmcnt(0)
	v_fmac_f32_e32 v30, v40, v48
	v_fmac_f32_e32 v30, v41, v49
	v_fmac_f32_e32 v30, v42, v50
	v_fmac_f32_e32 v30, v43, v51
	v_fmac_f32_e32 v30, v44, v52
	v_fmac_f32_e32 v30, v45, v53
	v_fmac_f32_e32 v30, v46, v54
	v_fmac_f32_e32 v30, v47, v55
	v_add_u32_e32 v35, 0xffffffe0, v35
	s_branch .Lhc1_a
.Lhc1_b:
	s_add_u32 s14, s12, 64
.Lhc1_b1:
	ds_read_b128 v[40:43], v33
	ds_read_b128 v[44:47], v33 offset:16
	ds_read2_b32 v[48:49], v34 offset0:7 offset1:6
	ds_read2_b32 v[50:51], v34 offset0:5 offset1:4
	ds_read2_b32 v[52:53], v34 offset0:3 offset1:2
	ds_read2_b32 v[54:55], v34 offset0:1 offset1:0
	v_add_u32_e32 v33, 32, v33
	v_add_u32_e32 v34, 0xffffffe0, v34
	s_add_u32 s13, s13, 8
	s_waitcnt lgkmcnt(0)
	v_cmp_le_i32_e32 vcc, 0, v35
	v_cndmask_b32_e32 v48, 0, v48, vcc
	v_fmac_f32_e32 v30, v40, v48
	v_cmp_le_i32_e32 vcc, 4, v35
	v_cndmask_b32_e32 v49, 0, v49, vcc
	v_fmac_f32_e32 v30, v41, v49
	v_cmp_le_i32_e32 vcc, 8, v35
	v_cndmask_b32_e32 v50, 0, v50, vcc
	v_fmac_f32_e32 v30, v42, v50
	v_cmp_le_i32_e32 vcc, 12, v35
	v_cndmask_b32_e32 v51, 0, v51, vcc
	v_fmac_f32_e32 v30, v43, v51
	v_cmp_le_i32_e32 vcc, 16, v35
	v_cndmask_b32_e32 v52, 0, v52, vcc
	v_fmac_f32_e32 v30, v44, v52
	v_cmp_le_i32_e32 vcc, 20, v35
	v_cndmask_b32_e32 v53, 0, v53, vcc
	v_fmac_f32_e32 v30, v45, v53
	v_cmp_le_i32_e32 vcc, 24, v35
	v_cndmask_b32_e32 v54, 0, v54, vcc
	v_fmac_f32_e32 v30, v46, v54
	v_cmp_le_i32_e32 vcc, 28, v35
	v_cndmask_b32_e32 v55, 0, v55, vcc
	v_fmac_f32_e32 v30, v47, v55
	v_add_u32_e32 v35, 0xffffffe0, v35
	s_cmp_lt_u32 s13, s14
	s_cbranch_scc1 .Lhc1_b1
	v_add3_u32 v33, v19, v21, 4
	v_mov_b32_e32 v34, 0xc24
	v_sub_u32_e32 v35, 0x3f8, v21
	s_sub_u32 s14, 0xc0, s12
	s_mov_b32 s13, 0
.Lhc1_c:
	s_cmp_ge_u32 s13, s14
	s_cbranch_scc1 .Lhc1_d
	ds_read2_b32 v[40:41], v34 offset0:0 offset1:1
	ds_read2_b32 v[42:43], v34 offset0:2 offset1:3
	ds_read2_b32 v[44:45], v34 offset0:4 offset1:5
	ds_read2_b32 v[46:47], v34 offset0:6 offset1:7
	ds_read2_b32 v[48:49], v33 offset0:0 offset1:1
	ds_read2_b32 v[50:51], v33 offset0:2 offset1:3
	ds_read2_b32 v[52:53], v33 offset0:4 offset1:5
	ds_read2_b32 v[54:55], v33 offset0:6 offset1:7
	v_add_u32_e32 v33, 32, v33
	v_add_u32_e32 v34, 32, v34
	s_add_u32 s13, s13, 8
	s_waitcnt lgkmcnt(0)
	v_fmac_f32_e32 v30, v40, v48
	v_fmac_f32_e32 v30, v41, v49
	v_fmac_f32_e32 v30, v42, v50
	v_fmac_f32_e32 v30, v43, v51
	v_fmac_f32_e32 v30, v44, v52
	v_fmac_f32_e32 v30, v45, v53
	v_fmac_f32_e32 v30, v46, v54
	v_fmac_f32_e32 v30, v47, v55
	v_add_u32_e32 v35, 0xffffffe0, v35
	s_branch .Lhc1_c
.Lhc1_d:
	s_add_u32 s14, s14, 64
.Lhc1_d1:
	ds_read2_b32 v[40:41], v34 offset0:0 offset1:1
	ds_read2_b32 v[42:43], v34 offset0:2 offset1:3
	ds_read2_b32 v[44:45], v34 offset0:4 offset1:5
	ds_read2_b32 v[46:47], v34 offset0:6 offset1:7
	ds_read2_b32 v[48:49], v33 offset0:0 offset1:1
	ds_read2_b32 v[50:51], v33 offset0:2 offset1:3
	ds_read2_b32 v[52:53], v33 offset0:4 offset1:5
	ds_read2_b32 v[54:55], v33 offset0:6 offset1:7
	v_add_u32_e32 v33, 32, v33
	v_add_u32_e32 v34, 32, v34
	s_add_u32 s13, s13, 8
	s_waitcnt lgkmcnt(0)
	v_cmp_le_i32_e32 vcc, 0, v35
	v_cndmask_b32_e32 v40, 0, v40, vcc
	v_fmac_f32_e32 v30, v40, v48
	v_cmp_le_i32_e32 vcc, 4, v35
	v_cndmask_b32_e32 v41, 0, v41, vcc
	v_fmac_f32_e32 v30, v41, v49
	v_cmp_le_i32_e32 vcc, 8, v35
	v_cndmask_b32_e32 v42, 0, v42, vcc
	v_fmac_f32_e32 v30, v42, v50
	v_cmp_le_i32_e32 vcc, 12, v35
	v_cndmask_b32_e32 v43, 0, v43, vcc
	v_fmac_f32_e32 v30, v43, v51
	v_cmp_le_i32_e32 vcc, 16, v35
	v_cndmask_b32_e32 v44, 0, v44, vcc
	v_fmac_f32_e32 v30, v44, v52
	v_cmp_le_i32_e32 vcc, 20, v35
	v_cndmask_b32_e32 v45, 0, v45, vcc
	v_fmac_f32_e32 v30, v45, v53
	v_cmp_le_i32_e32 vcc, 24, v35
	v_cndmask_b32_e32 v46, 0, v46, vcc
	v_fmac_f32_e32 v30, v46, v54
	v_cmp_le_i32_e32 vcc, 28, v35
	v_cndmask_b32_e32 v47, 0, v47, vcc
	v_fmac_f32_e32 v30, v47, v55
	v_add_u32_e32 v35, 0xffffffe0, v35
	s_cmp_lt_u32 s13, s14
	s_cbranch_scc1 .Lhc1_d1

.LBB0_966:
	v_readfirstlane_b32 s4, v21
	s_lshr_b32 s4, s4, 2
	v_mov_b32_e32 v33, v19
	v_mov_b32_e32 v35, v21
	v_add_u32_e32 v34, 0x804, v21
	s_mov_b32 s5, 0
.Lhc2_a:
	s_cmp_ge_u32 s5, s4
	s_cbranch_scc1 .Lhc2_b
	ds_read_b128 v[40:43], v33
	ds_read_b128 v[44:47], v33 offset:16
	ds_read2_b32 v[48:49], v34 offset0:7 offset1:6
	ds_read2_b32 v[50:51], v34 offset0:5 offset1:4
	ds_read2_b32 v[52:53], v34 offset0:3 offset1:2
	ds_read2_b32 v[54:55], v34 offset0:1 offset1:0
	v_add_u32_e32 v33, 32, v33
	v_add_u32_e32 v34, 0xffffffe0, v34
	s_add_u32 s5, s5, 8
	s_waitcnt lgkmcnt(0)
	v_fmac_f32_e32 v12, v40, v48
	v_fmac_f32_e32 v12, v41, v49
	v_fmac_f32_e32 v12, v42, v50
	v_fmac_f32_e32 v12, v43, v51
	v_fmac_f32_e32 v12, v44, v52
	v_fmac_f32_e32 v12, v45, v53
	v_fmac_f32_e32 v12, v46, v54
	v_fmac_f32_e32 v12, v47, v55
	v_add_u32_e32 v35, 0xffffffe0, v35
	s_branch .Lhc2_a
.Lhc2_b:
	s_add_u32 s6, s4, 64
.Lhc2_b1:
	ds_read_b128 v[40:43], v33
	ds_read_b128 v[44:47], v33 offset:16
	ds_read2_b32 v[48:49], v34 offset0:7 offset1:6
	ds_read2_b32 v[50:51], v34 offset0:5 offset1:4
	ds_read2_b32 v[52:53], v34 offset0:3 offset1:2
	ds_read2_b32 v[54:55], v34 offset0:1 offset1:0
	v_add_u32_e32 v33, 32, v33
	v_add_u32_e32 v34, 0xffffffe0, v34
	s_add_u32 s5, s5, 8
	s_waitcnt lgkmcnt(0)
	v_cmp_le_i32_e32 vcc, 0, v35
	v_cndmask_b32_e32 v48, 0, v48, vcc
	v_fmac_f32_e32 v12, v40, v48
	v_cmp_le_i32_e32 vcc, 4, v35
	v_cndmask_b32_e32 v49, 0, v49, vcc
	v_fmac_f32_e32 v12, v41, v49
	v_cmp_le_i32_e32 vcc, 8, v35
	v_cndmask_b32_e32 v50, 0, v50, vcc
	v_fmac_f32_e32 v12, v42, v50
	v_cmp_le_i32_e32 vcc, 12, v35
	v_cndmask_b32_e32 v51, 0, v51, vcc
	v_fmac_f32_e32 v12, v43, v51
	v_cmp_le_i32_e32 vcc, 16, v35
	v_cndmask_b32_e32 v52, 0, v52, vcc
	v_fmac_f32_e32 v12, v44, v52
	v_cmp_le_i32_e32 vcc, 20, v35
	v_cndmask_b32_e32 v53, 0, v53, vcc
	v_fmac_f32_e32 v12, v45, v53
	v_cmp_le_i32_e32 vcc, 24, v35
	v_cndmask_b32_e32 v54, 0, v54, vcc
	v_fmac_f32_e32 v12, v46, v54
	v_cmp_le_i32_e32 vcc, 28, v35
	v_cndmask_b32_e32 v55, 0, v55, vcc
	v_fmac_f32_e32 v12, v47, v55
	v_add_u32_e32 v35, 0xffffffe0, v35
	s_cmp_lt_u32 s5, s6
	s_cbranch_scc1 .Lhc2_b1
	v_add3_u32 v33, v19, v21, 4
	v_mov_b32_e32 v34, 0xc24
	v_sub_u32_e32 v35, 0x3f8, v21
	s_sub_u32 s6, 0xc0, s4
	s_mov_b32 s5, 0
.Lhc2_c:
	s_cmp_ge_u32 s5, s6
	s_cbranch_scc1 .Lhc2_d
	ds_read2_b32 v[40:41], v34 offset0:0 offset1:1
	ds_read2_b32 v[42:43], v34 offset0:2 offset1:3
	ds_read2_b32 v[44:45], v34 offset0:4 offset1:5
	ds_read2_b32 v[46:47], v34 offset0:6 offset1:7
	ds_read2_b32 v[48:49], v33 offset0:0 offset1:1
	ds_read2_b32 v[50:51], v33 offset0:2 offset1:3
	ds_read2_b32 v[52:53], v33 offset0:4 offset1:5
	ds_read2_b32 v[54:55], v33 offset0:6 offset1:7
	v_add_u32_e32 v33, 32, v33
	v_add_u32_e32 v34, 32, v34
	s_add_u32 s5, s5, 8
	s_waitcnt lgkmcnt(0)
	v_fmac_f32_e32 v12, v40, v48
	v_fmac_f32_e32 v12, v41, v49
	v_fmac_f32_e32 v12, v42, v50
	v_fmac_f32_e32 v12, v43, v51
	v_fmac_f32_e32 v12, v44, v52
	v_fmac_f32_e32 v12, v45, v53
	v_fmac_f32_e32 v12, v46, v54
	v_fmac_f32_e32 v12, v47, v55
	v_add_u32_e32 v35, 0xffffffe0, v35
	s_branch .Lhc2_c
.Lhc2_d:
	s_add_u32 s6, s6, 64
.Lhc2_d1:
	ds_read2_b32 v[40:41], v34 offset0:0 offset1:1
	ds_read2_b32 v[42:43], v34 offset0:2 offset1:3
	ds_read2_b32 v[44:45], v34 offset0:4 offset1:5
	ds_read2_b32 v[46:47], v34 offset0:6 offset1:7
	ds_read2_b32 v[48:49], v33 offset0:0 offset1:1
	ds_read2_b32 v[50:51], v33 offset0:2 offset1:3
	ds_read2_b32 v[52:53], v33 offset0:4 offset1:5
	ds_read2_b32 v[54:55], v33 offset0:6 offset1:7
	v_add_u32_e32 v33, 32, v33
	v_add_u32_e32 v34, 32, v34
	s_add_u32 s5, s5, 8
	s_waitcnt lgkmcnt(0)
	v_cmp_le_i32_e32 vcc, 0, v35
	v_cndmask_b32_e32 v40, 0, v40, vcc
	v_fmac_f32_e32 v12, v40, v48
	v_cmp_le_i32_e32 vcc, 4, v35
	v_cndmask_b32_e32 v41, 0, v41, vcc
	v_fmac_f32_e32 v12, v41, v49
	v_cmp_le_i32_e32 vcc, 8, v35
	v_cndmask_b32_e32 v42, 0, v42, vcc
	v_fmac_f32_e32 v12, v42, v50
	v_cmp_le_i32_e32 vcc, 12, v35
	v_cndmask_b32_e32 v43, 0, v43, vcc
	v_fmac_f32_e32 v12, v43, v51
	v_cmp_le_i32_e32 vcc, 16, v35
	v_cndmask_b32_e32 v44, 0, v44, vcc
	v_fmac_f32_e32 v12, v44, v52
	v_cmp_le_i32_e32 vcc, 20, v35
	v_cndmask_b32_e32 v45, 0, v45, vcc
	v_fmac_f32_e32 v12, v45, v53
	v_cmp_le_i32_e32 vcc, 24, v35
	v_cndmask_b32_e32 v46, 0, v46, vcc
	v_fmac_f32_e32 v12, v46, v54
	v_cmp_le_i32_e32 vcc, 28, v35
	v_cndmask_b32_e32 v47, 0, v47, vcc
	v_fmac_f32_e32 v12, v47, v55
	v_add_u32_e32 v35, 0xffffffe0, v35
	s_cmp_lt_u32 s5, s6
	s_cbranch_scc1 .Lhc2_d1
